# first grid barrier census: 16 per-XCC counter loads issued together with one wait instead of 16 serialized load+wait round trips
# baseline (speedup 1.0000x reference)
; __device__ __forceinline__ unsigned xb_ld(unsigned* p)              { return __hip_atomic_load(p, __ATOMIC_RELAXED, __HIP_MEMORY_SCOPE_AGENT); }
; __device__ __forceinline__ void xcd_barrier_complete(unsigned* bar, unsigned x, unsigned& nloc, unsigned& nx) {
;     ...
;     for (;;) {
;         sum = 0u; cnt = 0u; mine = 0u;
; #pragma unroll
;         for (unsigned j = 0; j < 16; ++j) { const unsigned c = xb_ld(&bar[XB_XCNT(j)]); sum += c; cnt += (c > 0u) ? 1u : 0u; mine = (j == x) ? c : mine; }
;         if (sum == G) break;
;         __builtin_amdgcn_s_sleep(1);
;         if ((++sp & 255u) == 0u) { if (xb_ld(&bar[XB_TMO])) break; if (sp > XB_SPIN_CAP) { atomicAdd(&bar[XB_TMO], 1u); break; } }
;     }
.LBB0_850:
	v_readlane_b32 s4, v254, 0
	v_readlane_b32 s5, v254, 1
	s_waitcnt lgkmcnt(0)
	global_load_dword v0, v33, s[84:85] sc1
	v_readlane_b32 s6, v253, 61
	s_nop 1
	global_load_dword v1, v33, s[4:5] sc1
	v_readlane_b32 s4, v254, 2
	v_readlane_b32 s5, v254, 3
	s_nop 4
	global_load_dword v2, v33, s[4:5] sc1
	v_readlane_b32 s4, v254, 4
	v_readlane_b32 s5, v254, 5
	s_nop 4
	global_load_dword v3, v33, s[4:5] sc1
	v_readlane_b32 s4, v254, 6
	v_readlane_b32 s5, v254, 7
	s_nop 4
	global_load_dword v4, v33, s[4:5] sc1
	v_readlane_b32 s4, v254, 8
	v_readlane_b32 s5, v254, 9
	s_nop 4
	global_load_dword v5, v33, s[4:5] sc1
	v_readlane_b32 s4, v254, 10
	v_readlane_b32 s5, v254, 11
	s_nop 4
	global_load_dword v6, v33, s[4:5] sc1
	v_readlane_b32 s4, v254, 12
	v_readlane_b32 s5, v254, 13
	s_nop 4
	global_load_dword v7, v33, s[4:5] sc1
	v_readlane_b32 s4, v254, 14
	v_readlane_b32 s5, v254, 15
	s_nop 4
	global_load_dword v8, v33, s[4:5] sc1
	v_readlane_b32 s4, v254, 16
	v_readlane_b32 s5, v254, 17
	s_nop 4
	global_load_dword v9, v33, s[4:5] sc1
	v_readlane_b32 s4, v254, 18
	v_readlane_b32 s5, v254, 19
	s_nop 4
	global_load_dword v10, v33, s[4:5] sc1
	v_readlane_b32 s4, v254, 20
	v_readlane_b32 s5, v254, 21
	s_nop 4
	global_load_dword v11, v33, s[4:5] sc1
	v_readlane_b32 s4, v254, 22
	v_readlane_b32 s5, v254, 23
	s_nop 4
	global_load_dword v12, v33, s[4:5] sc1
	v_readlane_b32 s4, v254, 24
	v_readlane_b32 s5, v254, 25
	s_nop 4
	global_load_dword v13, v33, s[4:5] sc1
	v_readlane_b32 s4, v254, 26
	v_readlane_b32 s5, v254, 27
	s_nop 4
	global_load_dword v14, v33, s[4:5] sc1
	v_readlane_b32 s4, v254, 28
	v_readlane_b32 s5, v254, 29
	s_nop 4
	global_load_dword v15, v33, s[4:5] sc1
	s_mov_b64 s[4:5], -1
	s_waitcnt vmcnt(0)
	v_add_u32_e32 v16, v1, v0
	v_add_u32_e32 v16, v16, v2
	v_add_u32_e32 v16, v16, v3
	v_add_u32_e32 v16, v16, v4
	v_add_u32_e32 v16, v16, v5
	v_add_u32_e32 v16, v16, v6
	v_add_u32_e32 v16, v16, v7
	v_add_u32_e32 v16, v16, v8
	v_add_u32_e32 v16, v16, v9
	v_add_u32_e32 v16, v16, v10
	v_add_u32_e32 v16, v16, v11
	v_add_u32_e32 v16, v16, v12
	v_add_u32_e32 v16, v16, v13
	v_add_u32_e32 v16, v16, v14
	v_add_u32_e32 v16, v16, v15
	v_cmp_eq_u32_e32 vcc, s6, v16
	s_mov_b64 s[6:7], -1
	s_cbranch_vccnz .LBB0_849
	s_and_b32 s4, s3, 0xff
	s_cmp_eq_u32 s4, 0
	s_mov_b64 s[4:5], -1
	s_mov_b64 s[8:9], -1
	s_sleep 1
	s_cbranch_scc0 .LBB0_854
	v_readlane_b32 s4, v253, 62
	v_readlane_b32 s5, v253, 63
	s_nop 4
	global_load_dword v16, v33, s[4:5] sc1
	s_waitcnt vmcnt(0)
	v_cmp_eq_u32_e32 vcc, 0, v16
	s_cbranch_vccnz .LBB0_856
	s_mov_b64 s[8:9], 0
	s_mov_b64 s[4:5], -1
